# attention: key order inside each 16-key block transposed (4x4 index transpose) so that the value waves transposed LDS reads are bank-conflict free
# speedup vs baseline: 1.0107x; 1.0107x over previous
.LBB0_382:
	s_andn2_b64 vcc, exec, s[4:5]
	s_cbranch_vccnz .LBB0_418
	s_and_b64 s[4:5], s[68:69], exec
	v_readlane_b32 s4, v255, 36
	s_cselect_b32 s3, 0x100, 0
	s_and_b32 s4, s4, 56
	s_and_b32 s5, s2, 0xffffffc0
	s_or_b32 s4, s4, s5
	s_bfe_u32 s5, s2, 0x30003
	s_or_b32 s20, s3, 0x800
	s_or_b32 s4, s4, s5
	s_cmpk_eq_i32 s76, 0x100
	s_cselect_b32 s21, s4, s2
	s_cmp_ge_i32 s21, s20
	s_cbranch_scc1 .LBB0_418
	s_add_u32 s6, s54, 0x11f80000
	s_addc_u32 s7, s55, 0
	s_lshl_b32 s22, s76, 1
	s_and_b64 s[4:5], s[68:69], exec
	s_cselect_b32 s23, 8, 0
	s_abs_i32 s24, s76
	s_waitcnt vmcnt(0)
	v_cvt_f32_u32_e32 v9, s24
	v_lshrrev_b32_e32 v5, 5, v158
	v_lshrrev_b32_e32 v0, 2, v219
	v_lshl_or_b32 v0, v0, 2, v5
	v_rcp_iflag_f32_e32 v9, v9
	v_mul_u32_u24_e32 v6, 0x148, v0
	v_lshlrev_b32_e32 v0, 2, v218
	v_and_b32_e32 v8, 12, v0
	v_mul_f32_e32 v9, 0x4f7ffffe, v9
	v_cvt_u32_f32_e32 v9, v9
	v_ashrrev_i32_e32 v0, 2, v160
	s_movk_i32 s4, 0x148
	s_sub_i32 s8, 0, s24
	v_readfirstlane_b32 s9, v9
	v_mul_lo_u32 v2, v0, s4
	v_and_b32_e32 v3, 3, v218
	s_movk_i32 s4, 0x50
	s_mul_i32 s8, s8, s9
	v_mad_u32_u24 v2, v3, s4, v2
	v_lshlrev_b32_e32 v0, 3, v0
	s_mul_hi_u32 s8, s9, s8
	v_and_b32_e32 v7, 16, v218
	v_lshlrev_b32_e32 v169, 4, v158
	v_lshlrev_b32_e32 v170, 1, v2
	v_sub_u32_e32 v2, v2, v0
	s_add_i32 s26, s9, s8
	v_readlane_b32 s8, v255, 29
	v_and_b32_e32 v4, 31, v218
	v_ashrrev_i32_e32 v3, 31, v2
	v_lshlrev_b32_e32 v0, 3, v5
	v_lshlrev_b32_e32 v5, 4, v5
	v_add_u32_e32 v172, s8, v169
	v_add3_u32 v6, v6, v7, v8
	s_movk_i32 s8, 0x290
	v_bfe_u32 v161, v218, 4, 1
	v_lshlrev_b32_e32 v168, 2, v4
	v_cmp_gt_u32_e64 s[4:5], 32, v158
	v_lshlrev_b32_e32 v171, 2, v158
	s_ashr_i32 s25, s76, 31
	v_lshl_add_u32 v173, v6, 1, 0
	v_and_b32_e32 v10, 3, v4
	v_lshlrev_b32_e32 v10, 2, v10
	v_bfe_u32 v11, v4, 2, 2
	v_and_or_b32 v10, v4, 16, v10
	v_or_b32_e32 v10, v10, v11
	v_mad_u32_u24 v174, v10, s8, v5
	v_lshlrev_b64 v[162:163], 1, v[2:3]
	v_lshlrev_b32_e32 v164, 1, v0
	s_branch .LBB0_387

.LBB0_397:
	s_lshl_b32 s8, s30, 2
	s_add_i32 s8, s8, -4
	s_and_b32 s8, s8, 4
	v_readlane_b32 s9, v255, 28
	s_or_b32 s8, s8, s9
	s_mulk_i32 s8, 0x1080
	s_add_i32 s8, s8, 0x1ec00
	v_add_u32_e32 v0, s8, v168
	ds_read_b32 v0, v0 offset:4096
	s_bfe_u32 s8, s18, 0x10002
	s_mulk_i32 s8, 0x4200
	s_add_i32 s8, s8, 0xfffffc00
	v_add_u32_e32 v2, s8, v172
	s_mul_hi_u32 s8, s19, 0xaaaaaaab
	s_lshr_b32 s8, s8, 1
	s_mul_i32 s8, s8, 0xfffe1400
	s_add_i32 s8, s8, 0xffff5c00
	v_add_u32_e32 v3, s8, v144
	ds_read_b128 v[176:179], v2
	ds_read_b128 v[180:183], v2 offset:1024
	ds_read_b128 v[184:187], v2 offset:2048
	ds_read_b128 v[188:191], v2 offset:3072
	ds_read_b64_tr_b16 v[220:221], v3
	ds_read_b64_tr_b16 v[222:223], v3 offset:1312
	ds_read_b64_tr_b16 v[224:225], v3 offset:64
	ds_read_b64_tr_b16 v[226:227], v3 offset:1376
	ds_read_b64_tr_b16 v[228:229], v3 offset:128
	ds_read_b64_tr_b16 v[230:231], v3 offset:1440
	ds_read_b64_tr_b16 v[232:233], v3 offset:192
	ds_read_b64_tr_b16 v[234:235], v3 offset:1504
	ds_read_b64_tr_b16 v[236:237], v3 offset:256
	ds_read_b64_tr_b16 v[238:239], v3 offset:1568
	s_waitcnt lgkmcnt(14)
	v_cmp_neq_f32_e32 vcc, 1.0, v0
	s_cbranch_vccz .Lav_noscale
	v_pk_mul_f32 v[142:143], v[0:1], v[142:143] op_sel_hi:[0,1]
	v_pk_mul_f32 v[140:141], v[0:1], v[140:141] op_sel_hi:[0,1]
	v_pk_mul_f32 v[138:139], v[0:1], v[138:139] op_sel_hi:[0,1]
	v_pk_mul_f32 v[136:137], v[0:1], v[136:137] op_sel_hi:[0,1]
	v_pk_mul_f32 v[134:135], v[0:1], v[134:135] op_sel_hi:[0,1]
	v_pk_mul_f32 v[132:133], v[0:1], v[132:133] op_sel_hi:[0,1]
	v_pk_mul_f32 v[130:131], v[0:1], v[130:131] op_sel_hi:[0,1]
	v_pk_mul_f32 v[128:129], v[0:1], v[128:129] op_sel_hi:[0,1]
	v_pk_mul_f32 v[126:127], v[0:1], v[126:127] op_sel_hi:[0,1]
	v_pk_mul_f32 v[124:125], v[0:1], v[124:125] op_sel_hi:[0,1]
	v_pk_mul_f32 v[122:123], v[0:1], v[122:123] op_sel_hi:[0,1]
	v_pk_mul_f32 v[120:121], v[0:1], v[120:121] op_sel_hi:[0,1]
	v_pk_mul_f32 v[118:119], v[0:1], v[118:119] op_sel_hi:[0,1]
	v_pk_mul_f32 v[116:117], v[0:1], v[116:117] op_sel_hi:[0,1]
	v_pk_mul_f32 v[114:115], v[0:1], v[114:115] op_sel_hi:[0,1]
	v_pk_mul_f32 v[112:113], v[0:1], v[112:113] op_sel_hi:[0,1]
	v_pk_mul_f32 v[110:111], v[0:1], v[110:111] op_sel_hi:[0,1]
	v_pk_mul_f32 v[108:109], v[0:1], v[108:109] op_sel_hi:[0,1]
	v_pk_mul_f32 v[106:107], v[0:1], v[106:107] op_sel_hi:[0,1]
	v_pk_mul_f32 v[104:105], v[0:1], v[104:105] op_sel_hi:[0,1]
	v_pk_mul_f32 v[102:103], v[0:1], v[102:103] op_sel_hi:[0,1]
	v_pk_mul_f32 v[100:101], v[0:1], v[100:101] op_sel_hi:[0,1]
	v_pk_mul_f32 v[98:99], v[0:1], v[98:99] op_sel_hi:[0,1]
	v_pk_mul_f32 v[96:97], v[0:1], v[96:97] op_sel_hi:[0,1]
	v_pk_mul_f32 v[94:95], v[0:1], v[94:95] op_sel_hi:[0,1]
	v_pk_mul_f32 v[92:93], v[0:1], v[92:93] op_sel_hi:[0,1]
	v_pk_mul_f32 v[90:91], v[0:1], v[90:91] op_sel_hi:[0,1]
	v_pk_mul_f32 v[88:89], v[0:1], v[88:89] op_sel_hi:[0,1]
	v_pk_mul_f32 v[86:87], v[0:1], v[86:87] op_sel_hi:[0,1]
	v_pk_mul_f32 v[84:85], v[0:1], v[84:85] op_sel_hi:[0,1]
	v_pk_mul_f32 v[82:83], v[0:1], v[82:83] op_sel_hi:[0,1]
	v_pk_mul_f32 v[80:81], v[0:1], v[80:81] op_sel_hi:[0,1]
	v_pk_mul_f32 v[78:79], v[0:1], v[78:79] op_sel_hi:[0,1]
	v_pk_mul_f32 v[76:77], v[0:1], v[76:77] op_sel_hi:[0,1]
	v_pk_mul_f32 v[74:75], v[0:1], v[74:75] op_sel_hi:[0,1]
	v_pk_mul_f32 v[72:73], v[0:1], v[72:73] op_sel_hi:[0,1]
	v_pk_mul_f32 v[70:71], v[0:1], v[70:71] op_sel_hi:[0,1]
	v_pk_mul_f32 v[68:69], v[0:1], v[68:69] op_sel_hi:[0,1]
	v_pk_mul_f32 v[66:67], v[0:1], v[66:67] op_sel_hi:[0,1]
	v_pk_mul_f32 v[64:65], v[0:1], v[64:65] op_sel_hi:[0,1]
	v_pk_mul_f32 v[62:63], v[0:1], v[62:63] op_sel_hi:[0,1]
	v_pk_mul_f32 v[60:61], v[0:1], v[60:61] op_sel_hi:[0,1]
	v_pk_mul_f32 v[58:59], v[0:1], v[58:59] op_sel_hi:[0,1]
	v_pk_mul_f32 v[56:57], v[0:1], v[56:57] op_sel_hi:[0,1]
	v_pk_mul_f32 v[54:55], v[0:1], v[54:55] op_sel_hi:[0,1]
	v_pk_mul_f32 v[52:53], v[0:1], v[52:53] op_sel_hi:[0,1]
	v_pk_mul_f32 v[50:51], v[0:1], v[50:51] op_sel_hi:[0,1]
	v_pk_mul_f32 v[48:49], v[0:1], v[48:49] op_sel_hi:[0,1]
	v_pk_mul_f32 v[46:47], v[0:1], v[46:47] op_sel_hi:[0,1]
	v_pk_mul_f32 v[44:45], v[0:1], v[44:45] op_sel_hi:[0,1]
	v_pk_mul_f32 v[42:43], v[0:1], v[42:43] op_sel_hi:[0,1]
	v_pk_mul_f32 v[40:41], v[0:1], v[40:41] op_sel_hi:[0,1]
	v_pk_mul_f32 v[38:39], v[0:1], v[38:39] op_sel_hi:[0,1]
	v_pk_mul_f32 v[36:37], v[0:1], v[36:37] op_sel_hi:[0,1]
	v_pk_mul_f32 v[34:35], v[0:1], v[34:35] op_sel_hi:[0,1]
	v_pk_mul_f32 v[32:33], v[0:1], v[32:33] op_sel_hi:[0,1]
	v_pk_mul_f32 v[30:31], v[0:1], v[30:31] op_sel_hi:[0,1]
	v_pk_mul_f32 v[28:29], v[0:1], v[28:29] op_sel_hi:[0,1]
	v_pk_mul_f32 v[26:27], v[0:1], v[26:27] op_sel_hi:[0,1]
	v_pk_mul_f32 v[24:25], v[0:1], v[24:25] op_sel_hi:[0,1]
	v_pk_mul_f32 v[22:23], v[0:1], v[22:23] op_sel_hi:[0,1]
	v_pk_mul_f32 v[20:21], v[0:1], v[20:21] op_sel_hi:[0,1]
	v_pk_mul_f32 v[18:19], v[0:1], v[18:19] op_sel_hi:[0,1]
	v_pk_mul_f32 v[16:17], v[0:1], v[16:17] op_sel_hi:[0,1]
.Lav_noscale:
	ds_read_b64_tr_b16 v[240:241], v3 offset:320
	ds_read_b64_tr_b16 v[242:243], v3 offset:1632
	ds_read_b64_tr_b16 v[244:245], v3 offset:384
	ds_read_b64_tr_b16 v[246:247], v3 offset:1696
	ds_read_b64_tr_b16 v[248:249], v3 offset:448
	ds_read_b64_tr_b16 v[250:251], v3 offset:1760
	s_waitcnt lgkmcnt(14)
	v_mfma_f32_32x32x16_bf16 v[128:143], v[220:223], v[176:179], v[128:143]
	ds_read_b64_tr_b16 v[220:221], v3 offset:10496
	ds_read_b64_tr_b16 v[222:223], v3 offset:11808
	s_waitcnt lgkmcnt(14)
	v_mfma_f32_32x32x16_bf16 v[112:127], v[224:227], v[176:179], v[112:127]
	ds_read_b64_tr_b16 v[224:225], v3 offset:10560
	ds_read_b64_tr_b16 v[226:227], v3 offset:11872
	s_waitcnt lgkmcnt(14)
	v_mfma_f32_32x32x16_bf16 v[96:111], v[228:231], v[176:179], v[96:111]
	ds_read_b64_tr_b16 v[228:229], v3 offset:10624
	ds_read_b64_tr_b16 v[230:231], v3 offset:11936
	s_waitcnt lgkmcnt(14)
	v_mfma_f32_32x32x16_bf16 v[80:95], v[232:235], v[176:179], v[80:95]
	ds_read_b64_tr_b16 v[232:233], v3 offset:10688
	ds_read_b64_tr_b16 v[234:235], v3 offset:12000
	s_waitcnt lgkmcnt(14)
	v_mfma_f32_32x32x16_bf16 v[64:79], v[236:239], v[176:179], v[64:79]
	ds_read_b64_tr_b16 v[236:237], v3 offset:10752
	ds_read_b64_tr_b16 v[238:239], v3 offset:12064
	s_waitcnt lgkmcnt(14)
	v_mfma_f32_32x32x16_bf16 v[48:63], v[240:243], v[176:179], v[48:63]
	ds_read_b64_tr_b16 v[240:241], v3 offset:10816
	ds_read_b64_tr_b16 v[242:243], v3 offset:12128
	s_waitcnt lgkmcnt(14)
	v_mfma_f32_32x32x16_bf16 v[32:47], v[244:247], v[176:179], v[32:47]
	ds_read_b64_tr_b16 v[244:245], v3 offset:10880
	ds_read_b64_tr_b16 v[246:247], v3 offset:12192
	s_waitcnt lgkmcnt(14)
	v_mfma_f32_32x32x16_bf16 v[16:31], v[248:251], v[176:179], v[16:31]
	ds_read_b64_tr_b16 v[248:249], v3 offset:10944
	ds_read_b64_tr_b16 v[250:251], v3 offset:12256
	s_waitcnt lgkmcnt(14)
	v_mfma_f32_32x32x16_bf16 v[128:143], v[220:223], v[180:183], v[128:143]
	ds_read_b64_tr_b16 v[220:221], v3 offset:20992
	ds_read_b64_tr_b16 v[222:223], v3 offset:22304
	s_waitcnt lgkmcnt(14)
	v_mfma_f32_32x32x16_bf16 v[112:127], v[224:227], v[180:183], v[112:127]
	ds_read_b64_tr_b16 v[224:225], v3 offset:21056
	ds_read_b64_tr_b16 v[226:227], v3 offset:22368
	s_waitcnt lgkmcnt(14)
	v_mfma_f32_32x32x16_bf16 v[96:111], v[228:231], v[180:183], v[96:111]
	ds_read_b64_tr_b16 v[228:229], v3 offset:21120
	ds_read_b64_tr_b16 v[230:231], v3 offset:22432
	s_waitcnt lgkmcnt(14)
	v_mfma_f32_32x32x16_bf16 v[80:95], v[232:235], v[180:183], v[80:95]
	ds_read_b64_tr_b16 v[232:233], v3 offset:21184
	ds_read_b64_tr_b16 v[234:235], v3 offset:22496
	s_waitcnt lgkmcnt(14)
	v_mfma_f32_32x32x16_bf16 v[64:79], v[236:239], v[180:183], v[64:79]
	ds_read_b64_tr_b16 v[236:237], v3 offset:21248
	ds_read_b64_tr_b16 v[238:239], v3 offset:22560
	s_waitcnt lgkmcnt(14)
	v_mfma_f32_32x32x16_bf16 v[48:63], v[240:243], v[180:183], v[48:63]
	ds_read_b64_tr_b16 v[240:241], v3 offset:21312
	ds_read_b64_tr_b16 v[242:243], v3 offset:22624
	s_waitcnt lgkmcnt(14)
	v_mfma_f32_32x32x16_bf16 v[32:47], v[244:247], v[180:183], v[32:47]
	ds_read_b64_tr_b16 v[244:245], v3 offset:21376
	ds_read_b64_tr_b16 v[246:247], v3 offset:22688
	s_waitcnt lgkmcnt(14)
	v_mfma_f32_32x32x16_bf16 v[16:31], v[248:251], v[180:183], v[16:31]
	ds_read_b64_tr_b16 v[248:249], v3 offset:21440
	ds_read_b64_tr_b16 v[250:251], v3 offset:22752
	s_waitcnt lgkmcnt(14)
	v_mfma_f32_32x32x16_bf16 v[128:143], v[220:223], v[184:187], v[128:143]
	ds_read_b64_tr_b16 v[220:221], v3 offset:31488
	ds_read_b64_tr_b16 v[222:223], v3 offset:32800
	s_waitcnt lgkmcnt(14)
	v_mfma_f32_32x32x16_bf16 v[112:127], v[224:227], v[184:187], v[112:127]
	ds_read_b64_tr_b16 v[224:225], v3 offset:31552
	ds_read_b64_tr_b16 v[226:227], v3 offset:32864
	s_waitcnt lgkmcnt(14)
	v_mfma_f32_32x32x16_bf16 v[96:111], v[228:231], v[184:187], v[96:111]
	ds_read_b64_tr_b16 v[228:229], v3 offset:31616
	ds_read_b64_tr_b16 v[230:231], v3 offset:32928
	s_waitcnt lgkmcnt(14)
	v_mfma_f32_32x32x16_bf16 v[80:95], v[232:235], v[184:187], v[80:95]
	ds_read_b64_tr_b16 v[232:233], v3 offset:31680
	ds_read_b64_tr_b16 v[234:235], v3 offset:32992
	s_waitcnt lgkmcnt(14)
	v_mfma_f32_32x32x16_bf16 v[64:79], v[236:239], v[184:187], v[64:79]
	ds_read_b64_tr_b16 v[236:237], v3 offset:31744
	ds_read_b64_tr_b16 v[238:239], v3 offset:33056
	s_waitcnt lgkmcnt(14)
	v_mfma_f32_32x32x16_bf16 v[48:63], v[240:243], v[184:187], v[48:63]
	ds_read_b64_tr_b16 v[240:241], v3 offset:31808
	ds_read_b64_tr_b16 v[242:243], v3 offset:33120
	s_waitcnt lgkmcnt(14)
	v_mfma_f32_32x32x16_bf16 v[32:47], v[244:247], v[184:187], v[32:47]
	ds_read_b64_tr_b16 v[244:245], v3 offset:31872
	ds_read_b64_tr_b16 v[246:247], v3 offset:33184
	s_waitcnt lgkmcnt(14)
	v_mfma_f32_32x32x16_bf16 v[16:31], v[248:251], v[184:187], v[16:31]
	ds_read_b64_tr_b16 v[248:249], v3 offset:31936
	ds_read_b64_tr_b16 v[250:251], v3 offset:33248
	s_waitcnt lgkmcnt(14)
	v_mfma_f32_32x32x16_bf16 v[128:143], v[220:223], v[188:191], v[128:143]
	s_waitcnt lgkmcnt(12)
	v_mfma_f32_32x32x16_bf16 v[112:127], v[224:227], v[188:191], v[112:127]
	s_waitcnt lgkmcnt(10)
	v_mfma_f32_32x32x16_bf16 v[96:111], v[228:231], v[188:191], v[96:111]
	s_waitcnt lgkmcnt(8)
	v_mfma_f32_32x32x16_bf16 v[80:95], v[232:235], v[188:191], v[80:95]
	s_waitcnt lgkmcnt(6)
	v_mfma_f32_32x32x16_bf16 v[64:79], v[236:239], v[188:191], v[64:79]
	s_waitcnt lgkmcnt(4)
	v_mfma_f32_32x32x16_bf16 v[48:63], v[240:243], v[188:191], v[48:63]
	s_waitcnt lgkmcnt(2)
	v_mfma_f32_32x32x16_bf16 v[32:47], v[244:247], v[188:191], v[32:47]
	s_waitcnt lgkmcnt(0)
	v_mfma_f32_32x32x16_bf16 v[16:31], v[248:251], v[188:191], v[16:31]
